# neighbourhood attention: redundant (clamped) key-row LDS-DMA pieces of the last row steps are no longer issued; row wait becomes vmcnt(0) from there
# baseline (speedup 1.0000x reference)
.LBB0_235:
	s_mul_hi_u32 s11, s8, 0x24924925
	s_sub_i32 s74, s8, s11
	s_lshr_b32 s74, s74, 1
	s_add_i32 s74, s74, s11
	s_lshr_b32 s11, s74, 2
	s_add_i32 s74, s6, s87
	s_add_i32 s76, s74, 8
	s_add_i32 s74, s87, 17
	s_cmp_gt_i32 s74, s95
	s_cselect_b32 s100, 1, 0
	s_min_i32 s74, s74, s95
	v_add_u32_e32 v66, s74, v65
	v_lshlrev_b32_e32 v68, 6, v66
	s_mul_i32 s11, s11, 0x1c000
	v_add_u32_e32 v66, v68, v141
	s_sub_i32 s11, s9, s11
	v_ashrrev_i32_e32 v67, 31, v66
	v_or_b32_e32 v68, v68, v145
	s_cmp_lg_u32 s100, 0
	s_cbranch_scc1 .Lna_w0
	s_waitcnt vmcnt(8) lgkmcnt(0)
	s_branch .Lna_wj

.Lna_wj:
	s_barrier
	v_lshlrev_b64 v[66:67], 11, v[66:67]
	v_ashrrev_i32_e32 v69, 31, v68
	s_add_i32 s11, s11, 0
	v_lshl_add_u64 v[66:67], v[150:151], 0, v[66:67]
	v_lshlrev_b64 v[68:69], 11, v[68:69]
	s_add_i32 s74, s11, 0x14000
	s_add_i32 s11, s11, 0x16000
	v_lshl_add_u64 v[68:69], v[152:153], 0, v[68:69]
	s_cmp_lg_u32 s100, 0
	s_cbranch_scc1 .Lna_nodma
	s_mov_b32 s75, m0
	s_mov_b32 m0, s74
	s_nop 0
	global_load_lds_dwordx4 v[66:67], off
	s_mov_b32 m0, s11
	s_nop 0
	global_load_lds_dwordx4 v[68:69], off
	s_mov_b32 m0, s75
